# P6: the 8 row scales (same row panel for all of a workgroup's tiles) computed once in the P6 preamble and parked in a lane-private LDS slot; epilogues read them back instead of 16 loads + sums + rsq p
# speedup vs baseline: 1.0010x; 1.0010x over previous
.LBB0_665:
	s_add_u32 s8, s92, 0x7200000
	s_addc_u32 s9, s93, 0
	s_add_u32 s10, s92, 0x10000
	s_addc_u32 s11, s93, 0
	s_lshl_b32 s2, s2, 5
	s_mov_b64 s[12:13], 0x80
	s_and_b32 s18, s2, 0x60
	s_add_i32 m0, s25, 0x18000
	v_lshl_add_u64 v[6:7], v[6:7], 0, s[12:13]
	s_lshl_b32 s15, s14, 13
	s_lshl_b32 s19, s18, 7
	s_waitcnt vmcnt(2)
	s_barrier
	global_load_lds_dwordx4 v[6:7], off
	v_lshl_add_u64 v[4:5], v[4:5], 0, s[12:13]
	s_add_i32 m0, s25, 0x1a000
	s_add_i32 s43, s25, 0x8000
	s_add_i32 s44, s25, 0xa000
	global_load_lds_dwordx4 v[4:5], off
	v_lshl_add_u64 v[0:1], v[0:1], 0, s[12:13]
	s_mov_b32 m0, s43
	s_add_u32 s16, s28, 0x80080
	global_load_lds_dwordx4 v[0:1], off
	v_lshl_add_u64 v[0:1], v[2:3], 0, s[12:13]
	s_mov_b32 m0, s44
	s_addc_u32 s17, s29, 0
	global_load_lds_dwordx4 v[0:1], off
	s_add_i32 m0, s25, 0x1c000
	v_lshl_add_u64 v[0:1], s[16:17], 0, v[134:135]
	global_load_lds_dwordx4 v[0:1], off
	v_lshl_add_u64 v[0:1], s[16:17], 0, v[130:131]
	s_add_i32 m0, s25, 0x1e000
	s_sext_i32_i16 s2, s0
	global_load_lds_dwordx4 v[0:1], off
	v_and_b32_e32 v0, 15, v129
	v_lshlrev_b32_e32 v1, 1, v11
	v_lshlrev_b32_e32 v2, 2, v129
	v_lshlrev_b32_e32 v3, 6, v129
	s_movk_i32 s0, 0x3c0
	v_lshl_or_b32 v148, s14, 6, v0
	v_lshl_or_b32 v0, v0, 6, v1
	v_and_b32_e32 v2, 32, v2
	v_and_or_b32 v1, v3, s0, v1
	v_bitop3_b32 v149, s19, v1, v2 bitop3:0xf6
	v_lshlrev_b32_e32 v1, 9, v129
	v_bitop3_b32 v0, v0, s15, v2 bitop3:0xde
	v_and_b32_e32 v1, 0x70000, v1
	v_lshlrev_b32_e32 v2, 12, v12
	v_or3_b32 v1, v9, v1, v2
	v_add_u32_e32 v138, v1, v10
	v_lshlrev_b32_e32 v1, 5, v8
	s_waitcnt vmcnt(6)
	s_cmpk_lt_u32 s1, 0x100
	v_and_b32_e32 v1, 0xf0000, v1
	s_cselect_b64 s[14:15], -1, 0
	v_or3_b32 v1, v9, v1, v2
	s_add_i32 s46, 0, 0x10000
	s_add_i32 s47, 0, 0x14000
	s_ashr_i32 s45, s96, 31
	v_or_b32_e32 v150, s18, v11
	v_mov_b32_e32 v139, v135
	v_add_u32_e32 v140, v1, v10
	v_mov_b32_e32 v141, v135
	v_mov_b64_e32 v[142:143], 0x580
	v_mov_b64_e32 v[144:145], 0x57f
	v_add_u32_e32 v151, s46, v149
	v_add_u32_e32 v152, s47, v149
	v_add_u32_e32 v153, 0, v0
	v_mov_b32_e32 v154, 0x358637bd
	s_movk_i32 s48, 0x2c00
	s_barrier
	v_lshl_add_u32 v146, s24, 8, v148
	v_lshlrev_b32_e32 v147, 5, v146
	v_add_u32_e32 v254, 0x1000, v147
	global_load_dwordx4 v[156:159], v147, s[10:11]
	global_load_dwordx4 v[160:163], v147, s[10:11] offset:16
	global_load_dwordx4 v[164:167], v147, s[10:11] offset:512
	global_load_dwordx4 v[168:171], v147, s[10:11] offset:528
	global_load_dwordx4 v[172:175], v147, s[10:11] offset:1024
	global_load_dwordx4 v[176:179], v147, s[10:11] offset:1040
	global_load_dwordx4 v[180:183], v147, s[10:11] offset:1536
	global_load_dwordx4 v[184:187], v147, s[10:11] offset:1552
	global_load_dwordx4 v[188:191], v254, s[10:11]
	global_load_dwordx4 v[192:195], v254, s[10:11] offset:16
	global_load_dwordx4 v[196:199], v254, s[10:11] offset:512
	global_load_dwordx4 v[200:203], v254, s[10:11] offset:528
	global_load_dwordx4 v[204:207], v254, s[10:11] offset:1024
	global_load_dwordx4 v[208:211], v254, s[10:11] offset:1040
	global_load_dwordx4 v[212:215], v254, s[10:11] offset:1536
	global_load_dwordx4 v[216:219], v254, s[10:11] offset:1552
	s_waitcnt vmcnt(0)
	v_add_f32_e32 v156, v156, v157
	v_add_f32_e32 v158, v158, v159
	v_add_f32_e32 v160, v160, v161
	v_add_f32_e32 v162, v162, v163
	v_add_f32_e32 v156, v156, v158
	v_add_f32_e32 v160, v160, v162
	v_add_f32_e32 v156, v156, v160
	v_fmamk_f32 v156, v156, 0x3a000000, v154
	v_rsq_f32_e32 v158, v156
	v_add_f32_e32 v164, v164, v165
	v_add_f32_e32 v166, v166, v167
	v_add_f32_e32 v168, v168, v169
	v_add_f32_e32 v170, v170, v171
	v_add_f32_e32 v164, v164, v166
	v_add_f32_e32 v168, v168, v170
	v_add_f32_e32 v164, v164, v168
	v_fmamk_f32 v164, v164, 0x3a000000, v154
	v_rsq_f32_e32 v159, v164
	v_add_f32_e32 v172, v172, v173
	v_add_f32_e32 v174, v174, v175
	v_add_f32_e32 v176, v176, v177
	v_add_f32_e32 v178, v178, v179
	v_add_f32_e32 v172, v172, v174
	v_add_f32_e32 v176, v176, v178
	v_add_f32_e32 v172, v172, v176
	v_fmamk_f32 v172, v172, 0x3a000000, v154
	v_rsq_f32_e32 v160, v172
	v_add_f32_e32 v180, v180, v181
	v_add_f32_e32 v182, v182, v183
	v_add_f32_e32 v184, v184, v185
	v_add_f32_e32 v186, v186, v187
	v_add_f32_e32 v180, v180, v182
	v_add_f32_e32 v184, v184, v186
	v_add_f32_e32 v180, v180, v184
	v_fmamk_f32 v180, v180, 0x3a000000, v154
	v_rsq_f32_e32 v161, v180
	v_add_f32_e32 v188, v188, v189
	v_add_f32_e32 v190, v190, v191
	v_add_f32_e32 v192, v192, v193
	v_add_f32_e32 v194, v194, v195
	v_add_f32_e32 v188, v188, v190
	v_add_f32_e32 v192, v192, v194
	v_add_f32_e32 v188, v188, v192
	v_fmamk_f32 v188, v188, 0x3a000000, v154
	v_rsq_f32_e32 v166, v188
	v_add_f32_e32 v196, v196, v197
	v_add_f32_e32 v198, v198, v199
	v_add_f32_e32 v200, v200, v201
	v_add_f32_e32 v202, v202, v203
	v_add_f32_e32 v196, v196, v198
	v_add_f32_e32 v200, v200, v202
	v_add_f32_e32 v196, v196, v200
	v_fmamk_f32 v196, v196, 0x3a000000, v154
	v_rsq_f32_e32 v167, v196
	v_add_f32_e32 v204, v204, v205
	v_add_f32_e32 v206, v206, v207
	v_add_f32_e32 v208, v208, v209
	v_add_f32_e32 v210, v210, v211
	v_add_f32_e32 v204, v204, v206
	v_add_f32_e32 v208, v208, v210
	v_add_f32_e32 v204, v204, v208
	v_fmamk_f32 v204, v204, 0x3a000000, v154
	v_rsq_f32_e32 v168, v204
	v_add_f32_e32 v212, v212, v213
	v_add_f32_e32 v214, v214, v215
	v_add_f32_e32 v216, v216, v217
	v_add_f32_e32 v218, v218, v219
	v_add_f32_e32 v212, v212, v214
	v_add_f32_e32 v216, v216, v218
	v_add_f32_e32 v212, v212, v216
	v_fmamk_f32 v212, v212, 0x3a000000, v154
	v_rsq_f32_e32 v169, v212
	v_lshlrev_b32_e32 v146, 5, v129
	v_add_u32_e32 v146, 0x20000, v146
	s_nop 0
	ds_write_b128 v146, v[158:161]
	ds_write_b128 v146, v[166:169] offset:16
	s_branch .LBB0_668

.LBB0_671:
	ds_read_b128 v[156:159], v151
	ds_read_b128 v[160:163], v151 offset:1024
	ds_read_b128 v[164:167], v151 offset:2048
	ds_read_b128 v[168:171], v151 offset:3072
	ds_read_b128 v[172:175], v152
	ds_read_b128 v[176:179], v152 offset:1024
	ds_read_b128 v[180:183], v152 offset:2048
	ds_read_b128 v[184:187], v152 offset:3072
	s_add_u32 s28, s26, 0xfff80080
	s_addc_u32 s29, s27, -1
	s_cmp_eq_u32 s53, 28
	s_cselect_b32 s31, s19, s29
	s_cselect_b32 s30, s49, s28
	s_cselect_b32 s29, s17, s52
	s_cselect_b32 s28, s50, s51
	s_add_u32 s100, s30, 0x80
	s_addc_u32 s101, s31, 0
	s_add_i32 m0, s25, 0xc000
	ds_read_b128 v[188:191], v153
	ds_read_b128 v[192:195], v153 offset:1024
	ds_read_b128 v[196:199], v153 offset:2048
	ds_read_b128 v[200:203], v153 offset:3072
	ds_read_b128 v[204:207], v153 offset:4096
	ds_read_b128 v[208:211], v153 offset:5120
	ds_read_b128 v[212:215], v153 offset:6144
	ds_read_b128 v[216:219], v153 offset:7168
	global_load_lds_dwordx4 v138, s[26:27]
	s_add_i32 m0, s25, 0xe000
	s_nop 0
	global_load_lds_dwordx4 v140, s[26:27]
	s_waitcnt vmcnt(8)
	s_waitcnt lgkmcnt(0)
	s_barrier
	s_waitcnt lgkmcnt(0)
	v_mfma_f32_16x16x32_bf16 v[116:119], v[156:159], v[188:191], v[116:119]
	v_mfma_f32_16x16x32_bf16 v[116:119], v[160:163], v[192:195], v[116:119]
	v_mfma_f32_16x16x32_bf16 v[112:115], v[164:167], v[188:191], v[112:115]
	v_mfma_f32_16x16x32_bf16 v[112:115], v[168:171], v[192:195], v[112:115]
	v_mfma_f32_16x16x32_bf16 v[96:99], v[164:167], v[196:199], v[96:99]
	v_mfma_f32_16x16x32_bf16 v[96:99], v[168:171], v[200:203], v[96:99]
	v_mfma_f32_16x16x32_bf16 v[100:103], v[156:159], v[196:199], v[100:103]
	v_mfma_f32_16x16x32_bf16 v[100:103], v[160:163], v[200:203], v[100:103]
	v_mfma_f32_16x16x32_bf16 v[84:87], v[156:159], v[204:207], v[84:87]
	v_mfma_f32_16x16x32_bf16 v[84:87], v[160:163], v[208:211], v[84:87]
	v_mfma_f32_16x16x32_bf16 v[80:83], v[164:167], v[204:207], v[80:83]
	v_mfma_f32_16x16x32_bf16 v[80:83], v[168:171], v[208:211], v[80:83]
	v_mfma_f32_16x16x32_bf16 v[64:67], v[164:167], v[212:215], v[64:67]
	v_mfma_f32_16x16x32_bf16 v[64:67], v[168:171], v[216:219], v[64:67]
	v_mfma_f32_16x16x32_bf16 v[68:71], v[156:159], v[212:215], v[68:71]
	v_mfma_f32_16x16x32_bf16 v[68:71], v[160:163], v[216:219], v[68:71]
	v_mfma_f32_16x16x32_bf16 v[124:127], v[172:175], v[188:191], v[124:127]
	v_mfma_f32_16x16x32_bf16 v[124:127], v[176:179], v[192:195], v[124:127]
	v_mfma_f32_16x16x32_bf16 v[120:123], v[180:183], v[188:191], v[120:123]
	v_mfma_f32_16x16x32_bf16 v[120:123], v[184:187], v[192:195], v[120:123]
	v_mfma_f32_16x16x32_bf16 v[104:107], v[180:183], v[196:199], v[104:107]
	v_mfma_f32_16x16x32_bf16 v[104:107], v[184:187], v[200:203], v[104:107]
	v_mfma_f32_16x16x32_bf16 v[108:111], v[172:175], v[196:199], v[108:111]
	v_mfma_f32_16x16x32_bf16 v[108:111], v[176:179], v[200:203], v[108:111]
	v_mfma_f32_16x16x32_bf16 v[92:95], v[172:175], v[204:207], v[92:95]
	v_mfma_f32_16x16x32_bf16 v[92:95], v[176:179], v[208:211], v[92:95]
	v_mfma_f32_16x16x32_bf16 v[88:91], v[180:183], v[204:207], v[88:91]
	v_mfma_f32_16x16x32_bf16 v[88:91], v[184:187], v[208:211], v[88:91]
	v_mfma_f32_16x16x32_bf16 v[72:75], v[180:183], v[212:215], v[72:75]
	v_mfma_f32_16x16x32_bf16 v[72:75], v[184:187], v[216:219], v[72:75]
	v_mfma_f32_16x16x32_bf16 v[76:79], v[172:175], v[212:215], v[76:79]
	v_mfma_f32_16x16x32_bf16 v[76:79], v[176:179], v[216:219], v[76:79]
	s_barrier
	s_add_i32 s54, s46, s36
	s_mov_b32 m0, s54
	ds_read_b128 v[188:191], v153 offset:16384
	ds_read_b128 v[192:195], v153 offset:17408
	ds_read_b128 v[196:199], v153 offset:18432
	ds_read_b128 v[200:203], v153 offset:19456
	ds_read_b128 v[204:207], v153 offset:20480
	ds_read_b128 v[208:211], v153 offset:21504
	ds_read_b128 v[212:215], v153 offset:22528
	ds_read_b128 v[216:219], v153 offset:23552
	global_load_lds_dwordx4 v134, s[28:29]
	s_add_i32 m0, s54, 0x2000
	s_add_u32 s54, s28, 0x80000
	s_addc_u32 s55, s29, 0
	s_add_i32 s56, s47, s36
	global_load_lds_dwordx4 v130, s[28:29]
	s_mov_b32 m0, s56
	s_nop 0
	global_load_lds_dwordx4 v134, s[54:55]
	s_add_i32 m0, s56, 0x2000
	s_nop 0
	global_load_lds_dwordx4 v130, s[54:55]
	s_mov_b32 m0, s25
	s_nop 0
	global_load_lds_dwordx4 v136, s[30:31]
	s_mov_b32 m0, s39
	s_nop 0
	global_load_lds_dwordx4 v132, s[30:31]
	s_waitcnt vmcnt(8)
	s_waitcnt lgkmcnt(0)
	s_barrier
	s_waitcnt lgkmcnt(0)
	v_mfma_f32_16x16x32_bf16 v[52:55], v[156:159], v[188:191], v[52:55]
	v_mfma_f32_16x16x32_bf16 v[52:55], v[160:163], v[192:195], v[52:55]
	v_mfma_f32_16x16x32_bf16 v[48:51], v[164:167], v[188:191], v[48:51]
	v_mfma_f32_16x16x32_bf16 v[48:51], v[168:171], v[192:195], v[48:51]
	v_mfma_f32_16x16x32_bf16 v[32:35], v[164:167], v[196:199], v[32:35]
	v_mfma_f32_16x16x32_bf16 v[32:35], v[168:171], v[200:203], v[32:35]
	v_mfma_f32_16x16x32_bf16 v[36:39], v[156:159], v[196:199], v[36:39]
	v_mfma_f32_16x16x32_bf16 v[36:39], v[160:163], v[200:203], v[36:39]
	v_mfma_f32_16x16x32_bf16 v[20:23], v[156:159], v[204:207], v[20:23]
	v_mfma_f32_16x16x32_bf16 v[20:23], v[160:163], v[208:211], v[20:23]
	v_mfma_f32_16x16x32_bf16 v[16:19], v[164:167], v[204:207], v[16:19]
	v_mfma_f32_16x16x32_bf16 v[16:19], v[168:171], v[208:211], v[16:19]
	v_mfma_f32_16x16x32_bf16 v[0:3], v[164:167], v[212:215], v[0:3]
	v_mfma_f32_16x16x32_bf16 v[0:3], v[168:171], v[216:219], v[0:3]
	v_mfma_f32_16x16x32_bf16 v[8:11], v[156:159], v[212:215], v[8:11]
	v_mfma_f32_16x16x32_bf16 v[8:11], v[160:163], v[216:219], v[8:11]
	v_mfma_f32_16x16x32_bf16 v[60:63], v[172:175], v[188:191], v[60:63]
	v_mfma_f32_16x16x32_bf16 v[60:63], v[176:179], v[192:195], v[60:63]
	v_mfma_f32_16x16x32_bf16 v[56:59], v[180:183], v[188:191], v[56:59]
	v_mfma_f32_16x16x32_bf16 v[56:59], v[184:187], v[192:195], v[56:59]
	v_mfma_f32_16x16x32_bf16 v[40:43], v[180:183], v[196:199], v[40:43]
	v_mfma_f32_16x16x32_bf16 v[40:43], v[184:187], v[200:203], v[40:43]
	v_mfma_f32_16x16x32_bf16 v[44:47], v[172:175], v[196:199], v[44:47]
	v_mfma_f32_16x16x32_bf16 v[44:47], v[176:179], v[200:203], v[44:47]
	v_mfma_f32_16x16x32_bf16 v[28:31], v[172:175], v[204:207], v[28:31]
	v_mfma_f32_16x16x32_bf16 v[28:31], v[176:179], v[208:211], v[28:31]
	v_mfma_f32_16x16x32_bf16 v[24:27], v[180:183], v[204:207], v[24:27]
	v_mfma_f32_16x16x32_bf16 v[24:27], v[184:187], v[208:211], v[24:27]
	v_mfma_f32_16x16x32_bf16 v[4:7], v[180:183], v[212:215], v[4:7]
	v_mfma_f32_16x16x32_bf16 v[4:7], v[184:187], v[216:219], v[4:7]
	v_mfma_f32_16x16x32_bf16 v[12:15], v[172:175], v[212:215], v[12:15]
	v_mfma_f32_16x16x32_bf16 v[12:15], v[176:179], v[216:219], v[12:15]
	s_barrier
	s_add_i32 s54, 0, 0x18000
	v_add_u32_e32 v155, s54, v149
	s_add_i32 s55, 0, 0x1c000
	ds_read_b128 v[156:159], v155
	ds_read_b128 v[160:163], v155 offset:1024
	ds_read_b128 v[164:167], v155 offset:2048
	ds_read_b128 v[168:171], v155 offset:3072
	v_add_u32_e32 v155, s55, v149
	ds_read_b128 v[172:175], v155
	ds_read_b128 v[176:179], v155 offset:1024
	ds_read_b128 v[180:183], v155 offset:2048
	ds_read_b128 v[184:187], v155 offset:3072
	s_add_u32 s30, s30, 0x80000
	s_addc_u32 s31, s31, 0
	s_mov_b32 m0, s40
	ds_read_b128 v[188:191], v153 offset:32768
	ds_read_b128 v[192:195], v153 offset:33792
	ds_read_b128 v[196:199], v153 offset:34816
	ds_read_b128 v[200:203], v153 offset:35840
	ds_read_b128 v[204:207], v153 offset:36864
	ds_read_b128 v[208:211], v153 offset:37888
	ds_read_b128 v[212:215], v153 offset:38912
	ds_read_b128 v[216:219], v153 offset:39936
	global_load_lds_dwordx4 v136, s[30:31]
	s_mov_b32 m0, s41
	s_nop 0
	global_load_lds_dwordx4 v132, s[30:31]
	s_waitcnt vmcnt(8)
	s_waitcnt lgkmcnt(0)
	s_barrier
	s_waitcnt lgkmcnt(0)
	v_mfma_f32_16x16x32_bf16 v[116:119], v[156:159], v[188:191], v[116:119]
	v_mfma_f32_16x16x32_bf16 v[116:119], v[160:163], v[192:195], v[116:119]
	v_mfma_f32_16x16x32_bf16 v[112:115], v[164:167], v[188:191], v[112:115]
	v_mfma_f32_16x16x32_bf16 v[112:115], v[168:171], v[192:195], v[112:115]
	v_mfma_f32_16x16x32_bf16 v[96:99], v[164:167], v[196:199], v[96:99]
	v_mfma_f32_16x16x32_bf16 v[96:99], v[168:171], v[200:203], v[96:99]
	v_mfma_f32_16x16x32_bf16 v[100:103], v[156:159], v[196:199], v[100:103]
	v_mfma_f32_16x16x32_bf16 v[100:103], v[160:163], v[200:203], v[100:103]
	v_mfma_f32_16x16x32_bf16 v[84:87], v[156:159], v[204:207], v[84:87]
	v_mfma_f32_16x16x32_bf16 v[84:87], v[160:163], v[208:211], v[84:87]
	v_mfma_f32_16x16x32_bf16 v[80:83], v[164:167], v[204:207], v[80:83]
	v_mfma_f32_16x16x32_bf16 v[80:83], v[168:171], v[208:211], v[80:83]
	v_mfma_f32_16x16x32_bf16 v[64:67], v[164:167], v[212:215], v[64:67]
	v_mfma_f32_16x16x32_bf16 v[64:67], v[168:171], v[216:219], v[64:67]
	v_mfma_f32_16x16x32_bf16 v[68:71], v[156:159], v[212:215], v[68:71]
	v_mfma_f32_16x16x32_bf16 v[68:71], v[160:163], v[216:219], v[68:71]
	v_mfma_f32_16x16x32_bf16 v[124:127], v[172:175], v[188:191], v[124:127]
	v_mfma_f32_16x16x32_bf16 v[124:127], v[176:179], v[192:195], v[124:127]
	v_mfma_f32_16x16x32_bf16 v[120:123], v[180:183], v[188:191], v[120:123]
	v_mfma_f32_16x16x32_bf16 v[120:123], v[184:187], v[192:195], v[120:123]
	v_mfma_f32_16x16x32_bf16 v[104:107], v[180:183], v[196:199], v[104:107]
	v_mfma_f32_16x16x32_bf16 v[104:107], v[184:187], v[200:203], v[104:107]
	v_mfma_f32_16x16x32_bf16 v[108:111], v[172:175], v[196:199], v[108:111]
	v_mfma_f32_16x16x32_bf16 v[108:111], v[176:179], v[200:203], v[108:111]
	v_mfma_f32_16x16x32_bf16 v[92:95], v[172:175], v[204:207], v[92:95]
	v_mfma_f32_16x16x32_bf16 v[92:95], v[176:179], v[208:211], v[92:95]
	v_mfma_f32_16x16x32_bf16 v[88:91], v[180:183], v[204:207], v[88:91]
	v_mfma_f32_16x16x32_bf16 v[88:91], v[184:187], v[208:211], v[88:91]
	v_mfma_f32_16x16x32_bf16 v[72:75], v[180:183], v[212:215], v[72:75]
	v_mfma_f32_16x16x32_bf16 v[72:75], v[184:187], v[216:219], v[72:75]
	v_mfma_f32_16x16x32_bf16 v[76:79], v[172:175], v[212:215], v[76:79]
	v_mfma_f32_16x16x32_bf16 v[76:79], v[176:179], v[216:219], v[76:79]
	s_barrier
	s_add_i32 s30, s54, s36
	s_add_u32 s98, s28, 0x80
	s_addc_u32 s99, s29, 0
	s_mov_b32 m0, s30
	ds_read_b128 v[188:191], v153 offset:49152
	ds_read_b128 v[192:195], v153 offset:50176
	ds_read_b128 v[196:199], v153 offset:51200
	ds_read_b128 v[200:203], v153 offset:52224
	ds_read_b128 v[204:207], v153 offset:53248
	ds_read_b128 v[208:211], v153 offset:54272
	ds_read_b128 v[212:215], v153 offset:55296
	ds_read_b128 v[216:219], v153 offset:56320
	global_load_lds_dwordx4 v134, s[98:99]
	s_add_i32 m0, s30, 0x2000
	s_add_u32 s28, s28, 0x80080
	s_addc_u32 s29, s29, 0
	s_add_i32 s30, s55, s36
	global_load_lds_dwordx4 v130, s[98:99]
	s_mov_b32 m0, s30
	s_nop 0
	global_load_lds_dwordx4 v134, s[28:29]
	s_add_i32 m0, s30, 0x2000
	s_nop 0
	global_load_lds_dwordx4 v130, s[28:29]
	s_mov_b32 m0, s43
	s_nop 0
	global_load_lds_dwordx4 v136, s[100:101]
	s_mov_b32 m0, s44
	s_nop 0
	global_load_lds_dwordx4 v132, s[100:101]
	s_waitcnt vmcnt(8)
	s_waitcnt lgkmcnt(0)
	s_barrier
	s_waitcnt lgkmcnt(0)
	v_mfma_f32_16x16x32_bf16 v[52:55], v[156:159], v[188:191], v[52:55]
	v_mfma_f32_16x16x32_bf16 v[52:55], v[160:163], v[192:195], v[52:55]
	v_mfma_f32_16x16x32_bf16 v[48:51], v[164:167], v[188:191], v[48:51]
	v_mfma_f32_16x16x32_bf16 v[48:51], v[168:171], v[192:195], v[48:51]
	v_mfma_f32_16x16x32_bf16 v[32:35], v[164:167], v[196:199], v[32:35]
	v_mfma_f32_16x16x32_bf16 v[32:35], v[168:171], v[200:203], v[32:35]
	v_mfma_f32_16x16x32_bf16 v[36:39], v[156:159], v[196:199], v[36:39]
	v_mfma_f32_16x16x32_bf16 v[36:39], v[160:163], v[200:203], v[36:39]
	v_mfma_f32_16x16x32_bf16 v[20:23], v[156:159], v[204:207], v[20:23]
	v_mfma_f32_16x16x32_bf16 v[20:23], v[160:163], v[208:211], v[20:23]
	v_mfma_f32_16x16x32_bf16 v[16:19], v[164:167], v[204:207], v[16:19]
	v_mfma_f32_16x16x32_bf16 v[16:19], v[168:171], v[208:211], v[16:19]
	v_mfma_f32_16x16x32_bf16 v[0:3], v[164:167], v[212:215], v[0:3]
	v_mfma_f32_16x16x32_bf16 v[0:3], v[168:171], v[216:219], v[0:3]
	v_mfma_f32_16x16x32_bf16 v[8:11], v[156:159], v[212:215], v[8:11]
	v_mfma_f32_16x16x32_bf16 v[8:11], v[160:163], v[216:219], v[8:11]
	v_mfma_f32_16x16x32_bf16 v[60:63], v[172:175], v[188:191], v[60:63]
	v_mfma_f32_16x16x32_bf16 v[60:63], v[176:179], v[192:195], v[60:63]
	v_mfma_f32_16x16x32_bf16 v[56:59], v[180:183], v[188:191], v[56:59]
	v_mfma_f32_16x16x32_bf16 v[56:59], v[184:187], v[192:195], v[56:59]
	v_mfma_f32_16x16x32_bf16 v[40:43], v[180:183], v[196:199], v[40:43]
	v_mfma_f32_16x16x32_bf16 v[40:43], v[184:187], v[200:203], v[40:43]
	v_mfma_f32_16x16x32_bf16 v[44:47], v[172:175], v[196:199], v[44:47]
	v_mfma_f32_16x16x32_bf16 v[44:47], v[176:179], v[200:203], v[44:47]
	v_mfma_f32_16x16x32_bf16 v[28:31], v[172:175], v[204:207], v[28:31]
	v_mfma_f32_16x16x32_bf16 v[28:31], v[176:179], v[208:211], v[28:31]
	v_mfma_f32_16x16x32_bf16 v[24:27], v[180:183], v[204:207], v[24:27]
	v_mfma_f32_16x16x32_bf16 v[24:27], v[184:187], v[208:211], v[24:27]
	v_mfma_f32_16x16x32_bf16 v[4:7], v[180:183], v[212:215], v[4:7]
	v_mfma_f32_16x16x32_bf16 v[4:7], v[184:187], v[216:219], v[4:7]
	v_mfma_f32_16x16x32_bf16 v[12:15], v[172:175], v[212:215], v[12:15]
	v_mfma_f32_16x16x32_bf16 v[12:15], v[176:179], v[216:219], v[12:15]
	s_barrier
	s_add_i32 s53, s53, 2
	s_add_u32 s26, s26, 0x100
	s_addc_u32 s27, s27, 0
	s_add_u32 s51, s51, 0x100
	s_addc_u32 s52, s52, 0
	s_cmp_gt_u32 s53, 29
	s_cbranch_scc0 .LBB0_671
	v_lshl_add_u32 v146, s24, 8, v148
	v_lshlrev_b32_e32 v147, 5, v129
	v_add_u32_e32 v147, 0x20000, v147
	ds_read_b128 v[156:159], v147
	ds_read_b128 v[160:163], v147 offset:16
	v_mul_u32_u24_e32 v155, 0x2c00, v146
	v_lshl_or_b32 v255, s2, 7, v150
	v_mov_b32_e32 v252, 0xbfb8aa3b
	v_mov_b32_e32 v253, 1.0
	v_lshl_add_u32 v155, v255, 1, v155
	v_pk_mul_f32 v[124:125], v[116:117], v[124:125]
	v_pk_mul_f32 v[126:127], v[118:119], v[126:127]
	v_pk_mul_f32 v[120:121], v[112:113], v[120:121]
	v_pk_mul_f32 v[122:123], v[114:115], v[122:123]
	v_pk_mul_f32 v[108:109], v[100:101], v[108:109]
	v_pk_mul_f32 v[110:111], v[102:103], v[110:111]
	v_pk_mul_f32 v[104:105], v[96:97], v[104:105]
	v_pk_mul_f32 v[106:107], v[98:99], v[106:107]
	v_pk_mul_f32 v[92:93], v[84:85], v[92:93]
	v_pk_mul_f32 v[94:95], v[86:87], v[94:95]
	v_pk_mul_f32 v[88:89], v[80:81], v[88:89]
	v_pk_mul_f32 v[90:91], v[82:83], v[90:91]
	v_pk_mul_f32 v[76:77], v[68:69], v[76:77]
	v_pk_mul_f32 v[78:79], v[70:71], v[78:79]
	v_pk_mul_f32 v[72:73], v[64:65], v[72:73]
	v_pk_mul_f32 v[74:75], v[66:67], v[74:75]
	v_pk_mul_f32 v[60:61], v[52:53], v[60:61]
	v_pk_mul_f32 v[62:63], v[54:55], v[62:63]
	v_pk_mul_f32 v[56:57], v[48:49], v[56:57]
	v_pk_mul_f32 v[58:59], v[50:51], v[58:59]
	v_pk_mul_f32 v[44:45], v[36:37], v[44:45]
	v_pk_mul_f32 v[46:47], v[38:39], v[46:47]
	v_pk_mul_f32 v[40:41], v[32:33], v[40:41]
	v_pk_mul_f32 v[42:43], v[34:35], v[42:43]
	v_pk_mul_f32 v[28:29], v[20:21], v[28:29]
	v_pk_mul_f32 v[30:31], v[22:23], v[30:31]
	v_pk_mul_f32 v[24:25], v[16:17], v[24:25]
	v_pk_mul_f32 v[26:27], v[18:19], v[26:27]
	v_pk_mul_f32 v[12:13], v[8:9], v[12:13]
	v_pk_mul_f32 v[14:15], v[10:11], v[14:15]
	v_pk_mul_f32 v[4:5], v[0:1], v[4:5]
	v_pk_mul_f32 v[6:7], v[2:3], v[6:7]
	s_and_b64 vcc, exec, s[14:15]
	s_cbranch_vccz .LBB0_674
	s_barrier
.LBB0_674:
	s_andn2_b64 vcc, exec, s[0:1]
	s_mov_b64 s[0:1], -1
	s_waitcnt lgkmcnt(0)
	v_mov_b32_e32 v147, v155
	v_mul_f32_e32 v254, v156, v156
	v_mul_f32_e32 v255, v156, v252
	v_pk_mul_f32 v[164:165], v[116:117], v[254:255] op_sel:[0,1]
	v_pk_mul_f32 v[166:167], v[118:119], v[254:255] op_sel:[0,1]
	v_pk_mul_f32 v[168:169], v[112:113], v[254:255] op_sel:[0,1]
	v_pk_mul_f32 v[170:171], v[114:115], v[254:255] op_sel:[0,1]
	v_exp_f32_e32 v164, v164
	v_exp_f32_e32 v165, v165
	v_exp_f32_e32 v166, v166
	v_exp_f32_e32 v167, v167
	v_exp_f32_e32 v168, v168
	v_exp_f32_e32 v169, v169
	v_exp_f32_e32 v170, v170
	v_exp_f32_e32 v171, v171
	v_pk_add_f32 v[164:165], v[164:165], v[252:253] op_sel:[0,1]
	v_pk_add_f32 v[166:167], v[166:167], v[252:253] op_sel:[0,1]
	v_pk_add_f32 v[168:169], v[168:169], v[252:253] op_sel:[0,1]
	v_pk_add_f32 v[170:171], v[170:171], v[252:253] op_sel:[0,1]
	v_rcp_f32_e32 v164, v164
	v_rcp_f32_e32 v165, v165
	v_rcp_f32_e32 v166, v166
	v_rcp_f32_e32 v167, v167
	v_rcp_f32_e32 v168, v168
	v_rcp_f32_e32 v169, v169
	v_rcp_f32_e32 v170, v170
	v_rcp_f32_e32 v171, v171
	v_pk_mul_f32 v[124:125], v[124:125], v[164:165]
	v_pk_mul_f32 v[126:127], v[126:127], v[166:167]
	v_pk_mul_f32 v[120:121], v[120:121], v[168:169]
	v_pk_mul_f32 v[122:123], v[122:123], v[170:171]
	v_pk_mul_f32 v[124:125], v[124:125], v[254:255] op_sel_hi:[1,0]
	v_pk_mul_f32 v[126:127], v[126:127], v[254:255] op_sel_hi:[1,0]
	v_pk_mul_f32 v[120:121], v[120:121], v[254:255] op_sel_hi:[1,0]
	v_pk_mul_f32 v[122:123], v[122:123], v[254:255] op_sel_hi:[1,0]
	v_cvt_pk_bf16_f32 v112, v124, v125
	v_cvt_pk_bf16_f32 v113, v126, v127
	v_cvt_pk_bf16_f32 v114, v120, v121
	v_cvt_pk_bf16_f32 v115, v122, v123
	global_store_dwordx4 v147, v[112:115], s[8:9]
	v_add_u32_e32 v147, 0x2c000, v155
	v_mul_f32_e32 v254, v157, v157
	v_mul_f32_e32 v255, v157, v252
	v_pk_mul_f32 v[164:165], v[100:101], v[254:255] op_sel:[0,1]
	v_pk_mul_f32 v[166:167], v[102:103], v[254:255] op_sel:[0,1]
	v_pk_mul_f32 v[168:169], v[96:97], v[254:255] op_sel:[0,1]
	v_pk_mul_f32 v[170:171], v[98:99], v[254:255] op_sel:[0,1]
	v_exp_f32_e32 v164, v164
	v_exp_f32_e32 v165, v165
	v_exp_f32_e32 v166, v166
	v_exp_f32_e32 v167, v167
	v_exp_f32_e32 v168, v168
	v_exp_f32_e32 v169, v169
	v_exp_f32_e32 v170, v170
	v_exp_f32_e32 v171, v171
	v_pk_add_f32 v[164:165], v[164:165], v[252:253] op_sel:[0,1]
	v_pk_add_f32 v[166:167], v[166:167], v[252:253] op_sel:[0,1]
	v_pk_add_f32 v[168:169], v[168:169], v[252:253] op_sel:[0,1]
	v_pk_add_f32 v[170:171], v[170:171], v[252:253] op_sel:[0,1]
	v_rcp_f32_e32 v164, v164
	v_rcp_f32_e32 v165, v165
	v_rcp_f32_e32 v166, v166
	v_rcp_f32_e32 v167, v167
	v_rcp_f32_e32 v168, v168
	v_rcp_f32_e32 v169, v169
	v_rcp_f32_e32 v170, v170
	v_rcp_f32_e32 v171, v171
	v_pk_mul_f32 v[108:109], v[108:109], v[164:165]
	v_pk_mul_f32 v[110:111], v[110:111], v[166:167]
	v_pk_mul_f32 v[104:105], v[104:105], v[168:169]
	v_pk_mul_f32 v[106:107], v[106:107], v[170:171]
	v_pk_mul_f32 v[108:109], v[108:109], v[254:255] op_sel_hi:[1,0]
	v_pk_mul_f32 v[110:111], v[110:111], v[254:255] op_sel_hi:[1,0]
	v_pk_mul_f32 v[104:105], v[104:105], v[254:255] op_sel_hi:[1,0]
	v_pk_mul_f32 v[106:107], v[106:107], v[254:255] op_sel_hi:[1,0]
	v_cvt_pk_bf16_f32 v96, v108, v109
	v_cvt_pk_bf16_f32 v97, v110, v111
	v_cvt_pk_bf16_f32 v98, v104, v105
	v_cvt_pk_bf16_f32 v99, v106, v107
	global_store_dwordx4 v147, v[96:99], s[8:9]
	v_add_u32_e32 v147, 0x58000, v155
	v_mul_f32_e32 v254, v158, v158
	v_mul_f32_e32 v255, v158, v252
	v_pk_mul_f32 v[164:165], v[84:85], v[254:255] op_sel:[0,1]
	v_pk_mul_f32 v[166:167], v[86:87], v[254:255] op_sel:[0,1]
	v_pk_mul_f32 v[168:169], v[80:81], v[254:255] op_sel:[0,1]
	v_pk_mul_f32 v[170:171], v[82:83], v[254:255] op_sel:[0,1]
	v_exp_f32_e32 v164, v164
	v_exp_f32_e32 v165, v165
	v_exp_f32_e32 v166, v166
	v_exp_f32_e32 v167, v167
	v_exp_f32_e32 v168, v168
	v_exp_f32_e32 v169, v169
	v_exp_f32_e32 v170, v170
	v_exp_f32_e32 v171, v171
	v_pk_add_f32 v[164:165], v[164:165], v[252:253] op_sel:[0,1]
	v_pk_add_f32 v[166:167], v[166:167], v[252:253] op_sel:[0,1]
	v_pk_add_f32 v[168:169], v[168:169], v[252:253] op_sel:[0,1]
	v_pk_add_f32 v[170:171], v[170:171], v[252:253] op_sel:[0,1]
	v_rcp_f32_e32 v164, v164
	v_rcp_f32_e32 v165, v165
	v_rcp_f32_e32 v166, v166
	v_rcp_f32_e32 v167, v167
	v_rcp_f32_e32 v168, v168
	v_rcp_f32_e32 v169, v169
	v_rcp_f32_e32 v170, v170
	v_rcp_f32_e32 v171, v171
	v_pk_mul_f32 v[92:93], v[92:93], v[164:165]
	v_pk_mul_f32 v[94:95], v[94:95], v[166:167]
	v_pk_mul_f32 v[88:89], v[88:89], v[168:169]
	v_pk_mul_f32 v[90:91], v[90:91], v[170:171]
	v_pk_mul_f32 v[92:93], v[92:93], v[254:255] op_sel_hi:[1,0]
	v_pk_mul_f32 v[94:95], v[94:95], v[254:255] op_sel_hi:[1,0]
	v_pk_mul_f32 v[88:89], v[88:89], v[254:255] op_sel_hi:[1,0]
	v_pk_mul_f32 v[90:91], v[90:91], v[254:255] op_sel_hi:[1,0]
	v_cvt_pk_bf16_f32 v80, v92, v93
	v_cvt_pk_bf16_f32 v81, v94, v95
	v_cvt_pk_bf16_f32 v82, v88, v89
	v_cvt_pk_bf16_f32 v83, v90, v91
	global_store_dwordx4 v147, v[80:83], s[8:9]
	v_add_u32_e32 v147, 0x84000, v155
	v_mul_f32_e32 v254, v159, v159
	v_mul_f32_e32 v255, v159, v252
	v_pk_mul_f32 v[164:165], v[68:69], v[254:255] op_sel:[0,1]
	v_pk_mul_f32 v[166:167], v[70:71], v[254:255] op_sel:[0,1]
	v_pk_mul_f32 v[168:169], v[64:65], v[254:255] op_sel:[0,1]
	v_pk_mul_f32 v[170:171], v[66:67], v[254:255] op_sel:[0,1]
	v_exp_f32_e32 v164, v164
	v_exp_f32_e32 v165, v165
	v_exp_f32_e32 v166, v166
	v_exp_f32_e32 v167, v167
	v_exp_f32_e32 v168, v168
	v_exp_f32_e32 v169, v169
	v_exp_f32_e32 v170, v170
	v_exp_f32_e32 v171, v171
	v_pk_add_f32 v[164:165], v[164:165], v[252:253] op_sel:[0,1]
	v_pk_add_f32 v[166:167], v[166:167], v[252:253] op_sel:[0,1]
	v_pk_add_f32 v[168:169], v[168:169], v[252:253] op_sel:[0,1]
	v_pk_add_f32 v[170:171], v[170:171], v[252:253] op_sel:[0,1]
	v_rcp_f32_e32 v164, v164
	v_rcp_f32_e32 v165, v165
	v_rcp_f32_e32 v166, v166
	v_rcp_f32_e32 v167, v167
	v_rcp_f32_e32 v168, v168
	v_rcp_f32_e32 v169, v169
	v_rcp_f32_e32 v170, v170
	v_rcp_f32_e32 v171, v171
	v_pk_mul_f32 v[76:77], v[76:77], v[164:165]
	v_pk_mul_f32 v[78:79], v[78:79], v[166:167]
	v_pk_mul_f32 v[72:73], v[72:73], v[168:169]
	v_pk_mul_f32 v[74:75], v[74:75], v[170:171]
	v_pk_mul_f32 v[76:77], v[76:77], v[254:255] op_sel_hi:[1,0]
	v_pk_mul_f32 v[78:79], v[78:79], v[254:255] op_sel_hi:[1,0]
	v_pk_mul_f32 v[72:73], v[72:73], v[254:255] op_sel_hi:[1,0]
	v_pk_mul_f32 v[74:75], v[74:75], v[254:255] op_sel_hi:[1,0]
	v_cvt_pk_bf16_f32 v64, v76, v77
	v_cvt_pk_bf16_f32 v65, v78, v79
	v_cvt_pk_bf16_f32 v66, v72, v73
	v_cvt_pk_bf16_f32 v67, v74, v75
	global_store_dwordx4 v147, v[64:67], s[8:9]
	v_add_u32_e32 v147, 0x160000, v155
	v_mul_f32_e32 v254, v160, v160
	v_mul_f32_e32 v255, v160, v252
	v_pk_mul_f32 v[164:165], v[52:53], v[254:255] op_sel:[0,1]
	v_pk_mul_f32 v[166:167], v[54:55], v[254:255] op_sel:[0,1]
	v_pk_mul_f32 v[168:169], v[48:49], v[254:255] op_sel:[0,1]
	v_pk_mul_f32 v[170:171], v[50:51], v[254:255] op_sel:[0,1]
	v_exp_f32_e32 v164, v164
	v_exp_f32_e32 v165, v165
	v_exp_f32_e32 v166, v166
	v_exp_f32_e32 v167, v167
	v_exp_f32_e32 v168, v168
	v_exp_f32_e32 v169, v169
	v_exp_f32_e32 v170, v170
	v_exp_f32_e32 v171, v171
	v_pk_add_f32 v[164:165], v[164:165], v[252:253] op_sel:[0,1]
	v_pk_add_f32 v[166:167], v[166:167], v[252:253] op_sel:[0,1]
	v_pk_add_f32 v[168:169], v[168:169], v[252:253] op_sel:[0,1]
	v_pk_add_f32 v[170:171], v[170:171], v[252:253] op_sel:[0,1]
	v_rcp_f32_e32 v164, v164
	v_rcp_f32_e32 v165, v165
	v_rcp_f32_e32 v166, v166
	v_rcp_f32_e32 v167, v167
	v_rcp_f32_e32 v168, v168
	v_rcp_f32_e32 v169, v169
	v_rcp_f32_e32 v170, v170
	v_rcp_f32_e32 v171, v171
	v_pk_mul_f32 v[60:61], v[60:61], v[164:165]
	v_pk_mul_f32 v[62:63], v[62:63], v[166:167]
	v_pk_mul_f32 v[56:57], v[56:57], v[168:169]
	v_pk_mul_f32 v[58:59], v[58:59], v[170:171]
	v_pk_mul_f32 v[60:61], v[60:61], v[254:255] op_sel_hi:[1,0]
	v_pk_mul_f32 v[62:63], v[62:63], v[254:255] op_sel_hi:[1,0]
	v_pk_mul_f32 v[56:57], v[56:57], v[254:255] op_sel_hi:[1,0]
	v_pk_mul_f32 v[58:59], v[58:59], v[254:255] op_sel_hi:[1,0]
	v_cvt_pk_bf16_f32 v48, v60, v61
	v_cvt_pk_bf16_f32 v49, v62, v63
	v_cvt_pk_bf16_f32 v50, v56, v57
	v_cvt_pk_bf16_f32 v51, v58, v59
	global_store_dwordx4 v147, v[48:51], s[8:9]
	v_add_u32_e32 v147, 0x18c000, v155
	v_mul_f32_e32 v254, v161, v161
	v_mul_f32_e32 v255, v161, v252
	v_pk_mul_f32 v[164:165], v[36:37], v[254:255] op_sel:[0,1]
	v_pk_mul_f32 v[166:167], v[38:39], v[254:255] op_sel:[0,1]
	v_pk_mul_f32 v[168:169], v[32:33], v[254:255] op_sel:[0,1]
	v_pk_mul_f32 v[170:171], v[34:35], v[254:255] op_sel:[0,1]
	v_exp_f32_e32 v164, v164
	v_exp_f32_e32 v165, v165
	v_exp_f32_e32 v166, v166
	v_exp_f32_e32 v167, v167
	v_exp_f32_e32 v168, v168
	v_exp_f32_e32 v169, v169
	v_exp_f32_e32 v170, v170
	v_exp_f32_e32 v171, v171
	v_pk_add_f32 v[164:165], v[164:165], v[252:253] op_sel:[0,1]
	v_pk_add_f32 v[166:167], v[166:167], v[252:253] op_sel:[0,1]
	v_pk_add_f32 v[168:169], v[168:169], v[252:253] op_sel:[0,1]
	v_pk_add_f32 v[170:171], v[170:171], v[252:253] op_sel:[0,1]
	v_rcp_f32_e32 v164, v164
	v_rcp_f32_e32 v165, v165
	v_rcp_f32_e32 v166, v166
	v_rcp_f32_e32 v167, v167
	v_rcp_f32_e32 v168, v168
	v_rcp_f32_e32 v169, v169
	v_rcp_f32_e32 v170, v170
	v_rcp_f32_e32 v171, v171
	v_pk_mul_f32 v[44:45], v[44:45], v[164:165]
	v_pk_mul_f32 v[46:47], v[46:47], v[166:167]
	v_pk_mul_f32 v[40:41], v[40:41], v[168:169]
	v_pk_mul_f32 v[42:43], v[42:43], v[170:171]
	v_pk_mul_f32 v[44:45], v[44:45], v[254:255] op_sel_hi:[1,0]
	v_pk_mul_f32 v[46:47], v[46:47], v[254:255] op_sel_hi:[1,0]
	v_pk_mul_f32 v[40:41], v[40:41], v[254:255] op_sel_hi:[1,0]
	v_pk_mul_f32 v[42:43], v[42:43], v[254:255] op_sel_hi:[1,0]
	v_cvt_pk_bf16_f32 v32, v44, v45
	v_cvt_pk_bf16_f32 v33, v46, v47
	v_cvt_pk_bf16_f32 v34, v40, v41
	v_cvt_pk_bf16_f32 v35, v42, v43
	global_store_dwordx4 v147, v[32:35], s[8:9]
	v_add_u32_e32 v147, 0x1b8000, v155
	v_mul_f32_e32 v254, v162, v162
	v_mul_f32_e32 v255, v162, v252
	v_pk_mul_f32 v[164:165], v[20:21], v[254:255] op_sel:[0,1]
	v_pk_mul_f32 v[166:167], v[22:23], v[254:255] op_sel:[0,1]
	v_pk_mul_f32 v[168:169], v[16:17], v[254:255] op_sel:[0,1]
	v_pk_mul_f32 v[170:171], v[18:19], v[254:255] op_sel:[0,1]
	v_exp_f32_e32 v164, v164
	v_exp_f32_e32 v165, v165
	v_exp_f32_e32 v166, v166
	v_exp_f32_e32 v167, v167
	v_exp_f32_e32 v168, v168
	v_exp_f32_e32 v169, v169
	v_exp_f32_e32 v170, v170
	v_exp_f32_e32 v171, v171
	v_pk_add_f32 v[164:165], v[164:165], v[252:253] op_sel:[0,1]
	v_pk_add_f32 v[166:167], v[166:167], v[252:253] op_sel:[0,1]
	v_pk_add_f32 v[168:169], v[168:169], v[252:253] op_sel:[0,1]
	v_pk_add_f32 v[170:171], v[170:171], v[252:253] op_sel:[0,1]
	v_rcp_f32_e32 v164, v164
	v_rcp_f32_e32 v165, v165
	v_rcp_f32_e32 v166, v166
	v_rcp_f32_e32 v167, v167
	v_rcp_f32_e32 v168, v168
	v_rcp_f32_e32 v169, v169
	v_rcp_f32_e32 v170, v170
	v_rcp_f32_e32 v171, v171
	v_pk_mul_f32 v[28:29], v[28:29], v[164:165]
	v_pk_mul_f32 v[30:31], v[30:31], v[166:167]
	v_pk_mul_f32 v[24:25], v[24:25], v[168:169]
	v_pk_mul_f32 v[26:27], v[26:27], v[170:171]
	v_pk_mul_f32 v[28:29], v[28:29], v[254:255] op_sel_hi:[1,0]
	v_pk_mul_f32 v[30:31], v[30:31], v[254:255] op_sel_hi:[1,0]
	v_pk_mul_f32 v[24:25], v[24:25], v[254:255] op_sel_hi:[1,0]
	v_pk_mul_f32 v[26:27], v[26:27], v[254:255] op_sel_hi:[1,0]
	v_cvt_pk_bf16_f32 v16, v28, v29
	v_cvt_pk_bf16_f32 v17, v30, v31
	v_cvt_pk_bf16_f32 v18, v24, v25
	v_cvt_pk_bf16_f32 v19, v26, v27
	global_store_dwordx4 v147, v[16:19], s[8:9]
	v_add_u32_e32 v147, 0x1e4000, v155
	v_mul_f32_e32 v254, v163, v163
	v_mul_f32_e32 v255, v163, v252
	v_pk_mul_f32 v[164:165], v[8:9], v[254:255] op_sel:[0,1]
	v_pk_mul_f32 v[166:167], v[10:11], v[254:255] op_sel:[0,1]
	v_pk_mul_f32 v[168:169], v[0:1], v[254:255] op_sel:[0,1]
	v_pk_mul_f32 v[170:171], v[2:3], v[254:255] op_sel:[0,1]
	v_exp_f32_e32 v164, v164
	v_exp_f32_e32 v165, v165
	v_exp_f32_e32 v166, v166
	v_exp_f32_e32 v167, v167
	v_exp_f32_e32 v168, v168
	v_exp_f32_e32 v169, v169
	v_exp_f32_e32 v170, v170
	v_exp_f32_e32 v171, v171
	v_pk_add_f32 v[164:165], v[164:165], v[252:253] op_sel:[0,1]
	v_pk_add_f32 v[166:167], v[166:167], v[252:253] op_sel:[0,1]
	v_pk_add_f32 v[168:169], v[168:169], v[252:253] op_sel:[0,1]
	v_pk_add_f32 v[170:171], v[170:171], v[252:253] op_sel:[0,1]
	v_rcp_f32_e32 v164, v164
	v_rcp_f32_e32 v165, v165
	v_rcp_f32_e32 v166, v166
	v_rcp_f32_e32 v167, v167
	v_rcp_f32_e32 v168, v168
	v_rcp_f32_e32 v169, v169
	v_rcp_f32_e32 v170, v170
	v_rcp_f32_e32 v171, v171
	v_pk_mul_f32 v[12:13], v[12:13], v[164:165]
	v_pk_mul_f32 v[14:15], v[14:15], v[166:167]
	v_pk_mul_f32 v[4:5], v[4:5], v[168:169]
	v_pk_mul_f32 v[6:7], v[6:7], v[170:171]
	v_pk_mul_f32 v[12:13], v[12:13], v[254:255] op_sel_hi:[1,0]
	v_pk_mul_f32 v[14:15], v[14:15], v[254:255] op_sel_hi:[1,0]
	v_pk_mul_f32 v[4:5], v[4:5], v[254:255] op_sel_hi:[1,0]
	v_pk_mul_f32 v[6:7], v[6:7], v[254:255] op_sel_hi:[1,0]
	v_cvt_pk_bf16_f32 v0, v12, v13
	v_cvt_pk_bf16_f32 v1, v14, v15
	v_cvt_pk_bf16_f32 v2, v4, v5
	v_cvt_pk_bf16_f32 v3, v6, v7
	global_store_dwordx4 v147, v[0:3], s[8:9]
	s_cbranch_vccnz .LBB0_667
	s_andn2_b64 vcc, exec, s[6:7]
	s_cbranch_vccnz .LBB0_666
	s_barrier
	s_branch .LBB0_666
